# v057 but the 8.5 us MERGE start offset is given to workgroups with bid bit 3 set (alternating inside each XCD) instead of odd bids
# speedup vs baseline: 1.0002x; 1.0002x over previous
.LBB0_1053:
	s_waitcnt lgkmcnt(0)
	s_barrier
	v_mbcnt_lo_u32_b32 v0, -1, 0
	v_mbcnt_hi_u32_b32 v0, -1, v0
	v_readlane_b32 s42, v255, 11
	s_mov_b32 s2, s55
	v_readlane_b32 s48, v255, 12
	s_mov_b32 s43, s84
	v_readlane_b32 s4, v255, 4
	v_readlane_b32 s6, v255, 6
	v_readlane_b32 s7, v255, 7
	s_and_b32 s41, s43, 1
	s_bfe_u32 s98, s43, 0x10003
	s_mov_b32 s10, s6
	s_mov_b32 s11, s7
	s_cmp_eq_u32 s98, 0
	v_readlane_b32 s5, v255, 5
	s_cbranch_scc1 .LBB0_1056
	s_memrealtime s[4:5]
	s_memrealtime s[0:1]
	v_mov_b64_e32 v[2:3], 0x351
	s_waitcnt lgkmcnt(0)
	s_sub_u32 s0, s0, s4
	s_subb_u32 s1, s1, s5
	v_cmp_gt_u64_e32 vcc, s[0:1], v[2:3]
	s_cbranch_vccnz .LBB0_1056
